# static priority: waves 4-7 run the pipelined global-attention loop at s_setprio 1 (one raise before the loop, reset after), code offsets of later loops kept modulo 128
# speedup vs baseline: 1.0175x; 1.0039x over previous
; #define LAS __attribute__((address_space(3)))
; __device__ __forceinline__ unsigned pk2(float lo, float hi) { f32x2_t v = {lo, hi}; bf16x2_t b = __builtin_convertvector(v, bf16x2_t); return __builtin_bit_cast(unsigned, b); }
; template <bool TRACK> ...
;     ...
;     { const int qrow = wave * 32 + r32; const bf16* qp = Qraw + (size_t)qrow * INW + hi * 8;
;       float qv[4][8]; float ss = 0.f;
; #pragma unroll
;       for (int d = 0; d < 4; ++d) { unpack8(*(const u32x4*)(qp + d * 16), qv[d]);
; #pragma unroll
;           for (int e = 0; e < 8; ++e) ss += qv[d][e] * qv[d][e]; }
;       ss += __shfl_xor(ss, 32);
;       const float rs = rsqrtf(ss * (1.0f / 64.0f) + 1e-6f) * (0.125f * LOG2E);
; #pragma unroll
;       for (int d = 0; d < 4; ++d) { const f32x4 w0 = *(const f32x4*)(qnw + d * 16 + hi * 8), w1 = *(const f32x4*)(qnw + d * 16 + hi * 8 + 4);
;           qv[d][0] *= rs * w0.x; qv[d][1] *= rs * w0.y; qv[d][2] *= rs * w0.z; qv[d][3] *= rs * w0.w; qv[d][4] *= rs * w1.x; qv[d][5] *= rs * w1.y; qv[d][6] *= rs * w1.z; qv[d][7] *= rs * w1.w; }
;       if (tpos0 >= 0) { const float* cp = ropet + (size_t)(tpos0 + qrow) * 32 + hi * 8; const float* sp = cp + 2048 * 32;
; #pragma unroll
;           for (int ax = 0; ax < 2; ++ax) { const f32x4 c0 = *(const f32x4*)(cp + ax * 16), c1 = *(const f32x4*)(cp + ax * 16 + 4), s0_ = *(const f32x4*)(sp + ax * 16), s1_ = *(const f32x4*)(sp + ax * 16 + 4);
;               const float cc[8] = {c0.x, c0.y, c0.z, c0.w, c1.x, c1.y, c1.z, c1.w}, sn[8] = {s0_.x, s0_.y, s0_.z, s0_.w, s1_.x, s1_.y, s1_.z, s1_.w};
; #pragma unroll
;               for (int e = 0; e < 8; ++e) { const float xa = qv[2 * ax][e], xb = qv[2 * ax + 1][e]; qv[2 * ax][e] = xa * cc[e] - xb * sn[e]; qv[2 * ax + 1][e] = xb * cc[e] + xa * sn[e]; } } }
; #pragma unroll
;       for (int d = 0; d < 4; ++d) { u32x4 w; w.x = pk2(qv[d][0], qv[d][1]); w.y = pk2(qv[d][2], qv[d][3]); w.z = pk2(qv[d][4], qv[d][5]); w.w = pk2(qv[d][6], qv[d][7]); qf[d] = __builtin_bit_cast(bf16x8, w); } }
;     __syncthreads();
;     *(LAS u32x4*)(lds + (srow * 72 + sc * 8) * 2) = kreg; { LAS u32x2* vw_ = (LAS u32x2*)(lds + 9216 + (srow * 68 + sc * 8) * 2); vw_[0] = (u32x2){vreg.x, vreg.y}; vw_[1] = (u32x2){vreg.z, vreg.w}; }
.LBB0_165:
	s_andn2_saveexec_b64 s[48:49], s[48:49]
	s_cbranch_execz .LBB0_169
	ds_bpermute_b32 v19, v188, v18
	s_mov_b32 s4, 0x800000
	s_add_i32 s51, s51, s73
	s_and_b32 s20, s51, 0x1fff
	s_mul_i32 s22, s20, 0x48000
	s_waitcnt lgkmcnt(0)
	v_add_f32_e32 v18, v18, v19
	v_fmamk_f32 v18, v18, 0x3c800000, v163
	v_cmp_gt_f32_e32 vcc, s4, v18
	v_mul_f32_e32 v19, 0x4b800000, v18
	s_add_u32 s20, s50, s22
	v_cndmask_b32_e32 v18, v18, v19, vcc
	v_rsq_f32_e32 v18, v18
	s_addc_u32 s21, 0, 0
	v_mov_b32_e32 v135, v1
	v_readlane_b32 s4, v250, 63
	v_mul_f32_e32 v19, 0x45800000, v18
	v_cndmask_b32_e32 v18, v18, v19, vcc
	v_mul_f32_e32 v70, 0x3e38aa3b, v18
	global_load_dwordx4 v[26:29], v[16:17], off offset:192
	global_load_dwordx4 v[18:21], v[16:17], off offset:144
	global_load_dwordx4 v[30:33], v[16:17], off offset:128
	global_load_dwordx4 v[72:75], v[16:17], off offset:16
	global_load_dwordx4 v[76:79], v[16:17], off
	global_load_dwordx4 v[80:83], v[16:17], off offset:80
	global_load_dwordx4 v[84:87], v[16:17], off offset:64
	global_load_dwordx4 v[88:91], v[22:23], off offset:16
	global_load_dwordx4 v[92:95], v[22:23], off
	global_load_dwordx4 v[96:99], v[14:15], off offset:16
	s_nop 0
	global_load_dwordx4 v[14:17], v[14:15], off
	s_waitcnt vmcnt(11)
	v_pk_mul_f32 v[10:11], v[10:11], v[70:71] op_sel_hi:[1,0]
	v_pk_mul_f32 v[12:13], v[12:13], v[70:71] op_sel_hi:[1,0]
	v_pk_mul_f32 v[40:41], v[10:11], v[40:41]
	v_pk_mul_f32 v[12:13], v[12:13], v[36:37]
	v_readlane_b32 s5, v249, 0
	s_waitcnt vmcnt(10)
	v_pk_mul_f32 v[26:27], v[26:27], v[70:71] op_sel_hi:[1,0]
	s_waitcnt vmcnt(9)
	v_pk_mul_f32 v[10:11], v[18:19], v[70:71] op_sel_hi:[1,0]
	v_pk_mul_f32 v[28:29], v[28:29], v[70:71] op_sel_hi:[1,0]
	v_pk_mul_f32 v[18:19], v[10:11], v[38:39]
	s_waitcnt vmcnt(6)
	v_pk_mul_f32 v[68:69], v[76:77], v[70:71] op_sel_hi:[1,0]
	s_nop 0
	v_pk_mul_f32 v[66:67], v[68:69], v[66:67]
	s_waitcnt vmcnt(4)
	v_pk_mul_f32 v[68:69], v[84:85], v[70:71] op_sel_hi:[1,0]
	s_nop 0
	v_pk_mul_f32 v[68:69], v[68:69], v[64:65]
	s_waitcnt vmcnt(0)
	v_pk_mul_f32 v[64:65], v[14:15], v[68:69]
	v_pk_mul_f32 v[14:15], v[14:15], v[66:67]
	v_pk_fma_f32 v[64:65], v[92:93], v[66:67], v[64:65] neg_lo:[0,0,1] neg_hi:[0,0,1]
	v_pk_fma_f32 v[66:67], v[92:93], v[68:69], v[14:15]
	v_pk_mul_f32 v[14:15], v[78:79], v[70:71] op_sel_hi:[1,0]
	s_nop 0
	v_pk_mul_f32 v[14:15], v[14:15], v[62:63]
	v_pk_mul_f32 v[62:63], v[86:87], v[70:71] op_sel_hi:[1,0]
	s_nop 0
	v_pk_mul_f32 v[62:63], v[62:63], v[60:61]
	s_nop 0
	v_pk_mul_f32 v[60:61], v[16:17], v[62:63]
	s_nop 0
	v_pk_fma_f32 v[60:61], v[94:95], v[14:15], v[60:61] neg_lo:[0,0,1] neg_hi:[0,0,1]
	v_pk_mul_f32 v[14:15], v[16:17], v[14:15]
	v_pk_mul_f32 v[16:17], v[80:81], v[70:71] op_sel_hi:[1,0]
	v_pk_fma_f32 v[62:63], v[94:95], v[62:63], v[14:15]
	v_pk_mul_f32 v[14:15], v[72:73], v[70:71] op_sel_hi:[1,0]
	v_pk_mul_f32 v[16:17], v[16:17], v[56:57]
	v_pk_mul_f32 v[14:15], v[14:15], v[58:59]
	v_pk_mul_f32 v[56:57], v[96:97], v[16:17]
	v_cvt_pk_bf16_f32 v94, v64, v65
	v_pk_fma_f32 v[56:57], v[88:89], v[14:15], v[56:57] neg_lo:[0,0,1] neg_hi:[0,0,1]
	v_pk_mul_f32 v[14:15], v[96:97], v[14:15]
	v_cvt_pk_bf16_f32 v95, v60, v61
	v_pk_fma_f32 v[58:59], v[88:89], v[16:17], v[14:15]
	v_pk_mul_f32 v[16:17], v[82:83], v[70:71] op_sel_hi:[1,0]
	v_pk_mul_f32 v[14:15], v[74:75], v[70:71] op_sel_hi:[1,0]
	v_pk_mul_f32 v[16:17], v[16:17], v[24:25]
	v_pk_mul_f32 v[14:15], v[14:15], v[54:55]
	v_pk_mul_f32 v[24:25], v[98:99], v[16:17]
	v_cvt_pk_bf16_f32 v92, v58, v59
	v_pk_fma_f32 v[54:55], v[90:91], v[14:15], v[24:25] neg_lo:[0,0,1] neg_hi:[0,0,1]
	v_pk_mul_f32 v[14:15], v[98:99], v[14:15]
	v_cvt_pk_bf16_f32 v96, v56, v57
	v_pk_fma_f32 v[68:69], v[90:91], v[16:17], v[14:15]
	global_load_dwordx4 v[14:17], v[22:23], off offset:80
	global_load_dwordx4 v[72:75], v[22:23], off offset:64
	s_nop 0
	global_load_dwordx4 v[22:25], v[42:43], off offset:16
	global_load_dwordx4 v[76:79], v[42:43], off
	v_pk_mul_f32 v[42:43], v[26:27], v[52:53]
	v_pk_mul_f32 v[26:27], v[30:31], v[70:71] op_sel_hi:[1,0]
	s_nop 0
	v_pk_mul_f32 v[30:31], v[26:27], v[50:51]
	s_barrier
	ds_write_b128 v45, v[2:5]
	ds_write2_b64 v71, v[6:7], v[8:9] offset1:1
	v_mov_b32_e32 v45, v1
	v_lshl_add_u64 v[2:3], s[20:21], 0, v[44:45]
	s_add_u32 s20, s45, s22
	v_lshl_add_u64 v[2:3], v[2:3], 0, v[134:135]
	s_addc_u32 s21, 0, 0
	v_lshl_add_u64 v[114:115], s[4:5], 0, v[2:3]
	v_lshl_add_u64 v[2:3], s[20:21], 0, v[134:135]
	v_readlane_b32 s4, v249, 1
	v_lshl_add_u64 v[2:3], v[2:3], 0, v[0:1]
	v_readlane_b32 s5, v249, 2
	s_waitcnt lgkmcnt(0)
	s_barrier
; template <bool TRACK> ...
;     ...
;     f32x16 o0, o1;
; #pragma unroll
;     for (int r = 0; r < 16; ++r) { o0[r] = 0.f; o1[r] = 0.f; }
;     float m = m_init, lsum = hi == 0 ? l_init : 0.f;
;     f32x16 negm, lacc;
; #pragma unroll
;     for (int r = 0; r < 16; ++r) { negm[r] = TRACK ? -m_init : 0.f; lacc[r] = TRACK ? 0.f : l_init * __builtin_amdgcn_exp2f(m_init); }
;     const bf16x8 ones = __builtin_bit_cast(bf16x8, ((u32x4){0x3f803f80u, 0x3f803f80u, 0x3f803f80u, 0x3f803f80u}));
;     for (int j = 0; j < nt; ++j) {
;         const int cur = j & 1; const int tl = j < n0 ? j : t1lo + (j - n0);
;         if (j + 1 < nt) { const int tn = (j + 1) < n0 ? (j + 1) : t1lo + (j + 1 - n0);
;             kreg = *(const u32x4*)(Kb + (size_t)(tn * 64 + srow) * 64 + sc * 8); vreg = *(const u32x4*)(Vtb + (size_t)srow * KEYS + tn * 64 + sc * 8); }
;         bool active = true; bool mt = masked && j >= n0; const int kpos0 = (tl - 4) * 64;
;         if (mt) { const int qs = qstart + wave * 32; active = !(kpos0 > qs + 31 + 128 || kpos0 + 63 < qs - 128);
;             if (kpos0 >= qs + 31 - 128 && kpos0 + 63 <= qs + 128) mt = false; }
;         if (active) {
;             const LAS unsigned char* Kbuf = lds + cur * 18432; const LAS unsigned char* Vbuf = Kbuf + 9216;
;             f32x16 s0 = negm, s1 = negm;
;             u32x2 vq[8];
;             if constexpr (!TRACK) {
;             bf16x8 kf[8];
; #pragma unroll
;             for (int d = 0; d < 4; ++d) { kf[2 * d] = *(const LAS bf16x8*)(Kbuf + (r32 * 72 + d * 16 + hi * 8) * 2); kf[2 * d + 1] = *(const LAS bf16x8*)(Kbuf + ((32 + r32) * 72 + d * 16 + hi * 8) * 2); }
;             __builtin_amdgcn_sched_barrier(0);
; #pragma unroll
;             for (int d = 0; d < 4; ++d) {
;                 s0 = __builtin_amdgcn_mfma_f32_32x32x16_bf16(kf[2 * d], qf[d], s0, 0, 0, 0);
;                 s1 = __builtin_amdgcn_mfma_f32_32x32x16_bf16(kf[2 * d + 1], qf[d], s1, 0, 0, 0);
;             }
; #pragma unroll
;             for (int kc = 0; kc < 2; ++kc) {
;                 const LAS unsigned char* vp0 = Vbuf + (r32 * 68 + kc * 16 + 4 * hi) * 2; const LAS unsigned char* vp1 = vp0 + 32 * 68 * 2;
;                 vq[4 * kc] = *(const LAS u32x2*)vp0; vq[4 * kc + 1] = *(const LAS u32x2*)(vp0 + 16); vq[4 * kc + 2] = *(const LAS u32x2*)vp1; vq[4 * kc + 3] = *(const LAS u32x2*)(vp1 + 16); }
;             __builtin_amdgcn_sched_barrier(0);
	v_lshl_add_u64 v[116:117], s[4:5], 0, v[2:3]
	global_load_dwordx4 v[230:233], v[114:115], off
	v_mov_b32_e32 v2, 0
	v_cvt_pk_bf16_f32 v90, v66, v67
	v_cvt_pk_bf16_f32 v91, v62, v63
	v_cvt_pk_bf16_f32 v93, v68, v69
	v_cvt_pk_bf16_f32 v97, v54, v55
	s_mov_b32 s20, 0
	v_mov_b32_e32 v3, v2
	v_mov_b32_e32 v4, v2
	v_mov_b32_e32 v5, v2
	v_mov_b32_e32 v6, v2
	v_mov_b32_e32 v7, v2
	v_mov_b32_e32 v8, v2
	v_mov_b32_e32 v9, v2
	v_mov_b32_e32 v36, v2
	v_mov_b32_e32 v37, v2
	v_mov_b32_e32 v38, v2
	v_mov_b32_e32 v39, v2
	v_mov_b32_e32 v44, v2
	v_mov_b32_e32 v45, v2
	s_mov_b64 s[4:5], 0x2000
	s_waitcnt vmcnt(2)
	v_pk_mul_f32 v[10:11], v[40:41], v[22:23]
	s_waitcnt vmcnt(1)
	v_pk_mul_f32 v[26:27], v[42:43], v[76:77]
	v_pk_fma_f32 v[10:11], v[18:19], v[14:15], v[10:11] neg_lo:[0,0,1] neg_hi:[0,0,1]
	v_pk_fma_f32 v[26:27], v[30:31], v[72:73], v[26:27] neg_lo:[0,0,1] neg_hi:[0,0,1]
	v_pk_mul_f32 v[30:31], v[30:31], v[76:77]
	v_pk_mul_f32 v[18:19], v[18:19], v[22:23]
	v_pk_fma_f32 v[30:31], v[42:43], v[72:73], v[30:31]
	v_pk_mul_f32 v[42:43], v[28:29], v[48:49]
	v_pk_mul_f32 v[28:29], v[32:33], v[70:71] op_sel_hi:[1,0]
	v_pk_fma_f32 v[14:15], v[40:41], v[14:15], v[18:19]
	v_pk_mul_f32 v[18:19], v[20:21], v[70:71] op_sel_hi:[1,0]
	v_pk_mul_f32 v[32:33], v[28:29], v[46:47]
	v_pk_mul_f32 v[28:29], v[42:43], v[78:79]
	v_pk_mul_f32 v[18:19], v[18:19], v[34:35]
	v_pk_mul_f32 v[20:21], v[12:13], v[24:25]
	v_pk_fma_f32 v[28:29], v[32:33], v[74:75], v[28:29] neg_lo:[0,0,1] neg_hi:[0,0,1]
	v_pk_mul_f32 v[32:33], v[32:33], v[78:79]
	v_pk_fma_f32 v[20:21], v[18:19], v[16:17], v[20:21] neg_lo:[0,0,1] neg_hi:[0,0,1]
	v_pk_mul_f32 v[18:19], v[18:19], v[24:25]
	v_pk_fma_f32 v[32:33], v[42:43], v[74:75], v[32:33]
	v_pk_fma_f32 v[12:13], v[12:13], v[16:17], v[18:19]
	v_cvt_pk_bf16_f32 v82, v30, v31
	v_cvt_pk_bf16_f32 v83, v32, v33
	v_cvt_pk_bf16_f32 v84, v14, v15
	v_cvt_pk_bf16_f32 v85, v12, v13
	v_cvt_pk_bf16_f32 v86, v26, v27
	v_cvt_pk_bf16_f32 v87, v28, v29
	v_cvt_pk_bf16_f32 v88, v10, v11
	v_cvt_pk_bf16_f32 v89, v20, v21
	v_mov_b32_e32 v10, v2
	v_mov_b32_e32 v11, v2
	v_mov_b32_e32 v12, v2
	v_mov_b32_e32 v13, v2
	v_mov_b32_e32 v14, v2
	v_mov_b32_e32 v15, v2
	v_mov_b32_e32 v16, v2
	v_mov_b32_e32 v17, v2
	v_mov_b32_e32 v18, v2
	v_mov_b32_e32 v19, v2
	v_mov_b32_e32 v20, v2
	v_mov_b32_e32 v21, v2
	v_mov_b32_e32 v22, v2
	v_mov_b32_e32 v23, v2
	v_mov_b32_e32 v24, v2
	v_mov_b32_e32 v25, v2
	v_mov_b32_e32 v26, v2
	v_mov_b32_e32 v27, v2
	v_mov_b32_e32 v28, v2
	v_mov_b32_e32 v29, v2
	v_mov_b32_e32 v30, v2
	v_mov_b32_e32 v31, v2
	v_mov_b32_e32 v32, v2
	v_mov_b32_e32 v33, v2
	v_mov_b32_e32 v34, v2
	v_mov_b32_e32 v35, v2
	v_mov_b32_e32 v40, v2
	v_mov_b32_e32 v41, v2
	v_mov_b32_e32 v42, v2
	v_mov_b32_e32 v43, v2
	v_mov_b32_e32 v46, v2
	v_mov_b32_e32 v47, v2
	v_mov_b32_e32 v48, v2
	v_mov_b32_e32 v49, v2
	s_waitcnt vmcnt(0)
	ds_write_b128 v201, v[230:233] offset:18432
	v_lshl_add_u64 v[114:115], v[114:115], 0, s[4:5]
	v_add_u32_e32 v246, v199, v200
	v_add_u32_e32 v127, 0x6c00, v203
	v_add_u32_e32 v129, 0x2400, v203
	v_mov_b32_e32 v118, s88
	v_mov_b32_e32 v119, s88
	v_mov_b32_e32 v120, s88
	v_mov_b32_e32 v121, s88
	v_add_u32_e32 v247, 0x2000, v246
	v_add_u32_e32 v0, 0x3000, v246
	v_add_u32_e32 v123, 0x6800, v246
	v_add_u32_e32 v125, 0x7800, v246
	s_waitcnt lgkmcnt(0)
	ds_read_b128 v[214:217], v204 offset:0
	ds_read_b128 v[218:221], v202 offset:0
	ds_read_b128 v[222:225], v204 offset:32
	ds_read_b128 v[226:229], v202 offset:32
	ds_read_b128 v[230:233], v204 offset:64
	ds_read_b128 v[234:237], v202 offset:64
	ds_read_b128 v[238:241], v204 offset:96
	ds_read_b128 v[242:245], v202 offset:96
	s_waitcnt lgkmcnt(7)
	v_mfma_f32_32x32x16_bf16 v[50:65], v[214:217], v[94:97], 0
	s_waitcnt lgkmcnt(6)
	v_mfma_f32_32x32x16_bf16 v[66:81], v[218:221], v[94:97], 0
	s_waitcnt lgkmcnt(5)
	v_mfma_f32_32x32x16_bf16 v[50:65], v[222:225], v[90:93], v[50:65]
	s_waitcnt lgkmcnt(4)
	v_mfma_f32_32x32x16_bf16 v[66:81], v[226:229], v[90:93], v[66:81]
	s_waitcnt lgkmcnt(3)
	v_mfma_f32_32x32x16_bf16 v[50:65], v[230:233], v[86:89], v[50:65]
	s_waitcnt lgkmcnt(2)
	v_mfma_f32_32x32x16_bf16 v[66:81], v[234:237], v[86:89], v[66:81]
	s_waitcnt lgkmcnt(1)
	v_mfma_f32_32x32x16_bf16 v[50:65], v[238:241], v[82:85], v[50:65]
	s_waitcnt lgkmcnt(0)
	v_mfma_f32_32x32x16_bf16 v[66:81], v[242:245], v[82:85], v[66:81]
	s_barrier
	s_nop 15
	v_exp_f32_e32 v50, v50
	v_exp_f32_e32 v51, v51
	v_exp_f32_e32 v52, v52
	v_exp_f32_e32 v53, v53
	v_exp_f32_e32 v54, v54
	v_exp_f32_e32 v55, v55
	v_exp_f32_e32 v56, v56
	v_exp_f32_e32 v57, v57
	v_cvt_pk_bf16_f32 v50, v50, v51
	v_cvt_pk_bf16_f32 v51, v52, v53
	v_cvt_pk_bf16_f32 v52, v54, v55
	v_cvt_pk_bf16_f32 v53, v56, v57
	v_readfirstlane_b32 s4, v114
	v_readfirstlane_b32 s5, v115
	v_readfirstlane_b32 s38, v116
	v_readfirstlane_b32 s39, v117
	s_nop 4
	v_subrev_u32_e32 v114, s4, v114
	v_subrev_u32_e32 v116, s38, v116
	s_nop 1
	v_readfirstlane_b32 s89, v187
	s_cmpk_lt_u32 s89, 0x100
	s_cbranch_scc1 .Lnoprio_a
	s_setprio 1
; template <bool TRACK> ...
;     ...
;         const int cur = j & 1; const int tl = j < n0 ? j : t1lo + (j - n0);
;         if (j + 1 < nt) { const int tn = (j + 1) < n0 ? (j + 1) : t1lo + (j + 1 - n0);
;             kreg = *(const u32x4*)(Kb + (size_t)(tn * 64 + srow) * 64 + sc * 8); vreg = *(const u32x4*)(Vtb + (size_t)srow * KEYS + tn * 64 + sc * 8); }
;         bool active = true; bool mt = masked && j >= n0; const int kpos0 = (tl - 4) * 64;
;         if (mt) { const int qs = qstart + wave * 32; active = !(kpos0 > qs + 31 + 128 || kpos0 + 63 < qs - 128);
;             if (kpos0 >= qs + 31 - 128 && kpos0 + 63 <= qs + 128) mt = false; }
;         if (active) {
;             const LAS unsigned char* Kbuf = lds + cur * 18432; const LAS unsigned char* Vbuf = Kbuf + 9216;
;             f32x16 s0 = negm, s1 = negm;
;             u32x2 vq[8];
;             if constexpr (!TRACK) {
;             bf16x8 kf[8];
; #pragma unroll
;             for (int d = 0; d < 4; ++d) { kf[2 * d] = *(const LAS bf16x8*)(Kbuf + (r32 * 72 + d * 16 + hi * 8) * 2); kf[2 * d + 1] = *(const LAS bf16x8*)(Kbuf + ((32 + r32) * 72 + d * 16 + hi * 8) * 2); }
;             __builtin_amdgcn_sched_barrier(0);
; #pragma unroll
;             for (int d = 0; d < 4; ++d) {
;                 s0 = __builtin_amdgcn_mfma_f32_32x32x16_bf16(kf[2 * d], qf[d], s0, 0, 0, 0);
;                 s1 = __builtin_amdgcn_mfma_f32_32x32x16_bf16(kf[2 * d + 1], qf[d], s1, 0, 0, 0);
;             }
; #pragma unroll
;             for (int kc = 0; kc < 2; ++kc) {
;                 const LAS unsigned char* vp0 = Vbuf + (r32 * 68 + kc * 16 + 4 * hi) * 2; const LAS unsigned char* vp1 = vp0 + 32 * 68 * 2;
;                 vq[4 * kc] = *(const LAS u32x2*)vp0; vq[4 * kc + 1] = *(const LAS u32x2*)(vp0 + 16); vq[4 * kc + 2] = *(const LAS u32x2*)vp1; vq[4 * kc + 3] = *(const LAS u32x2*)(vp1 + 16); }
;             __builtin_amdgcn_sched_barrier(0);
;             } else {
; #pragma unroll
;             for (int d = 0; d < 4; ++d) {
;                 const bf16x8 a0 = *(const LAS bf16x8*)(Kbuf + (r32 * 72 + d * 16 + hi * 8) * 2);
;                 const bf16x8 a1 = *(const LAS bf16x8*)(Kbuf + ((32 + r32) * 72 + d * 16 + hi * 8) * 2);
;                 s0 = __builtin_amdgcn_mfma_f32_32x32x16_bf16(a0, qf[d], s0, 0, 0, 0);
;                 s1 = __builtin_amdgcn_mfma_f32_32x32x16_bf16(a1, qf[d], s1, 0, 0, 0);
;             }
;     ...
; #pragma unroll
.Lnoprio_a:
.LBB0_167:
	global_load_dwordx4 v[98:101], v114, s[4:5]
	global_load_dwordx4 v[102:105], v116, s[38:39]
	ds_read_b128 v[106:109], v204 offset:18432
	ds_read_b128 v[110:113], v202 offset:18432
	ds_read_b128 v[158:161], v204 offset:18464
	ds_read2_b64 v[206:209], v247 offset0:128 offset1:130
	ds_read2_b64 v[210:213], v0 offset0:160 offset1:162
	s_add_u32 s4, s4, 0x2000
	s_addc_u32 s5, s5, 0
	s_add_u32 s38, s38, 0x80
	s_addc_u32 s39, s39, 0
	s_waitcnt lgkmcnt(4)
	v_mfma_f32_32x32x16_bf16 v[214:229], v[106:109], v[94:97], 0
	ds_read_b128 v[106:109], v202 offset:18464
	v_exp_f32_e32 v58, v58
	v_exp_f32_e32 v59, v59
	v_exp_f32_e32 v60, v60
	s_waitcnt lgkmcnt(4)
	v_mfma_f32_32x32x16_bf16 v[230:245], v[110:113], v[94:97], 0
	ds_read_b128 v[110:113], v204 offset:18496
	v_exp_f32_e32 v61, v61
	v_exp_f32_e32 v62, v62
	v_exp_f32_e32 v63, v63
	s_waitcnt lgkmcnt(4)
	v_mfma_f32_32x32x16_bf16 v[214:229], v[158:161], v[90:93], v[214:229]
	ds_read_b128 v[158:161], v202 offset:18496
	v_exp_f32_e32 v64, v64
	v_exp_f32_e32 v65, v65
	v_cvt_pk_bf16_f32 v54, v58, v59
	s_waitcnt lgkmcnt(2)
	v_mfma_f32_32x32x16_bf16 v[230:245], v[106:109], v[90:93], v[230:245]
	ds_read_b128 v[106:109], v204 offset:18528
	v_cvt_pk_bf16_f32 v55, v60, v61
	v_cvt_pk_bf16_f32 v56, v62, v63
	v_cvt_pk_bf16_f32 v57, v64, v65
	s_waitcnt lgkmcnt(2)
	v_mfma_f32_32x32x16_bf16 v[214:229], v[110:113], v[86:89], v[214:229]
	ds_read_b128 v[110:113], v202 offset:18528
	v_exp_f32_e32 v66, v66
	v_exp_f32_e32 v67, v67
	v_exp_f32_e32 v68, v68
	s_waitcnt lgkmcnt(2)
	v_mfma_f32_32x32x16_bf16 v[230:245], v[158:161], v[86:89], v[230:245]
	v_exp_f32_e32 v69, v69
	v_exp_f32_e32 v70, v70
	v_exp_f32_e32 v71, v71
	s_waitcnt lgkmcnt(1)
	v_mfma_f32_32x32x16_bf16 v[214:229], v[106:109], v[82:85], v[214:229]
	v_exp_f32_e32 v72, v72
	v_exp_f32_e32 v73, v73
	v_cvt_pk_bf16_f32 v66, v66, v67
	s_waitcnt lgkmcnt(0)
	v_mfma_f32_32x32x16_bf16 v[230:245], v[110:113], v[82:85], v[230:245]
	v_cvt_pk_bf16_f32 v67, v68, v69
	v_cvt_pk_bf16_f32 v68, v70, v71
	v_cvt_pk_bf16_f32 v69, v72, v73
	v_mfma_f32_32x32x16_bf16 v[2:17], v[206:209], v[50:53], v[2:17]
	ds_read2_b64 v[206:209], v247 offset0:132 offset1:134
	v_exp_f32_e32 v74, v74
	v_exp_f32_e32 v75, v75
	v_exp_f32_e32 v76, v76
	v_mfma_f32_32x32x16_bf16 v[18:33], v[210:213], v[50:53], v[18:33]
	ds_read2_b64 v[210:213], v0 offset0:164 offset1:166
	v_exp_f32_e32 v77, v77
	v_exp_f32_e32 v78, v78
	v_exp_f32_e32 v79, v79
	v_mfma_f32_4x4x4_16b_bf16 v[34:37], v[118:119], v[50:51], v[34:37]
	v_mfma_f32_4x4x4_16b_bf16 v[38:41], v[118:119], v[52:53], v[38:41]
	v_exp_f32_e32 v80, v80
	v_exp_f32_e32 v81, v81
	s_waitcnt lgkmcnt(1)
	v_mfma_f32_32x32x16_bf16 v[2:17], v[206:209], v[54:57], v[2:17]
	ds_read2_b64 v[206:209], v247 offset0:136 offset1:138
	v_cvt_pk_bf16_f32 v70, v74, v75
	v_cvt_pk_bf16_f32 v71, v76, v77
	v_cvt_pk_bf16_f32 v72, v78, v79
	s_waitcnt lgkmcnt(1)
	v_mfma_f32_32x32x16_bf16 v[18:33], v[210:213], v[54:57], v[18:33]
	ds_read2_b64 v[210:213], v0 offset0:168 offset1:170
	v_cvt_pk_bf16_f32 v73, v80, v81
	v_mfma_f32_4x4x4_16b_bf16 v[34:37], v[118:119], v[54:55], v[34:37]
	v_mfma_f32_4x4x4_16b_bf16 v[38:41], v[118:119], v[56:57], v[38:41]
	s_waitcnt vmcnt(1)
	ds_write_b128 v201, v[98:101] offset:0
	s_waitcnt vmcnt(0)
	ds_write2_b64 v127, v[102:103], v[104:105] offset1:1
	s_waitcnt lgkmcnt(3)
	v_mfma_f32_32x32x16_bf16 v[2:17], v[206:209], v[66:69], v[2:17]
	ds_read2_b64 v[206:209], v247 offset0:140 offset1:142
	v_exp_f32_e32 v214, v214
	v_exp_f32_e32 v215, v215
	v_exp_f32_e32 v216, v216
	s_waitcnt lgkmcnt(3)
	v_mfma_f32_32x32x16_bf16 v[18:33], v[210:213], v[66:69], v[18:33]
	ds_read2_b64 v[210:213], v0 offset0:172 offset1:174
	v_exp_f32_e32 v217, v217
	v_exp_f32_e32 v218, v218
	v_mfma_f32_4x4x4_16b_bf16 v[34:37], v[118:119], v[66:67], v[34:37]
	v_mfma_f32_4x4x4_16b_bf16 v[38:41], v[118:119], v[68:69], v[38:41]
	s_waitcnt lgkmcnt(1)
	v_mfma_f32_32x32x16_bf16 v[2:17], v[206:209], v[70:73], v[2:17]
	v_exp_f32_e32 v219, v219
	v_exp_f32_e32 v220, v220
	v_exp_f32_e32 v221, v221
	s_waitcnt lgkmcnt(0)
	v_mfma_f32_32x32x16_bf16 v[18:33], v[210:213], v[70:73], v[18:33]
	v_cvt_pk_bf16_f32 v214, v214, v215
	v_cvt_pk_bf16_f32 v215, v216, v217
	v_cvt_pk_bf16_f32 v216, v218, v219
	v_mfma_f32_4x4x4_16b_bf16 v[34:37], v[118:119], v[70:71], v[34:37]
	v_mfma_f32_4x4x4_16b_bf16 v[38:41], v[118:119], v[72:73], v[38:41]
	v_cvt_pk_bf16_f32 v217, v220, v221
	s_waitcnt lgkmcnt(0)
	s_barrier
; template <bool TRACK> ...
;     ...
;         const int cur = j & 1; const int tl = j < n0 ? j : t1lo + (j - n0);
;         if (j + 1 < nt) { const int tn = (j + 1) < n0 ? (j + 1) : t1lo + (j + 1 - n0);
;             kreg = *(const u32x4*)(Kb + (size_t)(tn * 64 + srow) * 64 + sc * 8); vreg = *(const u32x4*)(Vtb + (size_t)srow * KEYS + tn * 64 + sc * 8); }
;         bool active = true; bool mt = masked && j >= n0; const int kpos0 = (tl - 4) * 64;
;         if (mt) { const int qs = qstart + wave * 32; active = !(kpos0 > qs + 31 + 128 || kpos0 + 63 < qs - 128);
;             if (kpos0 >= qs + 31 - 128 && kpos0 + 63 <= qs + 128) mt = false; }
;         if (active) {
;             const LAS unsigned char* Kbuf = lds + cur * 18432; const LAS unsigned char* Vbuf = Kbuf + 9216;
;             f32x16 s0 = negm, s1 = negm;
;             u32x2 vq[8];
;             if constexpr (!TRACK) {
;             bf16x8 kf[8];
; #pragma unroll
;             for (int d = 0; d < 4; ++d) { kf[2 * d] = *(const LAS bf16x8*)(Kbuf + (r32 * 72 + d * 16 + hi * 8) * 2); kf[2 * d + 1] = *(const LAS bf16x8*)(Kbuf + ((32 + r32) * 72 + d * 16 + hi * 8) * 2); }
;             __builtin_amdgcn_sched_barrier(0);
; #pragma unroll
;             for (int d = 0; d < 4; ++d) {
;                 s0 = __builtin_amdgcn_mfma_f32_32x32x16_bf16(kf[2 * d], qf[d], s0, 0, 0, 0);
;                 s1 = __builtin_amdgcn_mfma_f32_32x32x16_bf16(kf[2 * d + 1], qf[d], s1, 0, 0, 0);
;             }
; #pragma unroll
;             for (int kc = 0; kc < 2; ++kc) {
;                 const LAS unsigned char* vp0 = Vbuf + (r32 * 68 + kc * 16 + 4 * hi) * 2; const LAS unsigned char* vp1 = vp0 + 32 * 68 * 2;
;                 vq[4 * kc] = *(const LAS u32x2*)vp0; vq[4 * kc + 1] = *(const LAS u32x2*)(vp0 + 16); vq[4 * kc + 2] = *(const LAS u32x2*)vp1; vq[4 * kc + 3] = *(const LAS u32x2*)(vp1 + 16); }
;             __builtin_amdgcn_sched_barrier(0);
;             } else {
; #pragma unroll
;             for (int d = 0; d < 4; ++d) {
;                 const bf16x8 a0 = *(const LAS bf16x8*)(Kbuf + (r32 * 72 + d * 16 + hi * 8) * 2);
;                 const bf16x8 a1 = *(const LAS bf16x8*)(Kbuf + ((32 + r32) * 72 + d * 16 + hi * 8) * 2);
;                 s0 = __builtin_amdgcn_mfma_f32_32x32x16_bf16(a0, qf[d], s0, 0, 0, 0);
;                 s1 = __builtin_amdgcn_mfma_f32_32x32x16_bf16(a1, qf[d], s1, 0, 0, 0);
;             }
;     ...
; #pragma unroll
	global_load_dwordx4 v[98:101], v114, s[4:5]
	global_load_dwordx4 v[102:105], v116, s[38:39]
	ds_read_b128 v[106:109], v204 offset:0
	ds_read_b128 v[110:113], v202 offset:0
	ds_read_b128 v[158:161], v204 offset:32
	ds_read2_b64 v[206:209], v123 offset0:128 offset1:130
	ds_read2_b64 v[210:213], v125 offset0:160 offset1:162
	s_add_u32 s4, s4, 0x2000
	s_addc_u32 s5, s5, 0
	s_add_u32 s38, s38, 0x80
	s_addc_u32 s39, s39, 0
	s_waitcnt lgkmcnt(4)
	v_mfma_f32_32x32x16_bf16 v[50:65], v[106:109], v[94:97], 0
	ds_read_b128 v[106:109], v202 offset:32
	v_exp_f32_e32 v222, v222
	v_exp_f32_e32 v223, v223
	v_exp_f32_e32 v224, v224
	s_waitcnt lgkmcnt(4)
	v_mfma_f32_32x32x16_bf16 v[66:81], v[110:113], v[94:97], 0
	ds_read_b128 v[110:113], v204 offset:64
	v_exp_f32_e32 v225, v225
	v_exp_f32_e32 v226, v226
	v_exp_f32_e32 v227, v227
	s_waitcnt lgkmcnt(4)
	v_mfma_f32_32x32x16_bf16 v[50:65], v[158:161], v[90:93], v[50:65]
	ds_read_b128 v[158:161], v202 offset:64
	v_exp_f32_e32 v228, v228
	v_exp_f32_e32 v229, v229
	v_cvt_pk_bf16_f32 v218, v222, v223
	s_waitcnt lgkmcnt(2)
	v_mfma_f32_32x32x16_bf16 v[66:81], v[106:109], v[90:93], v[66:81]
	ds_read_b128 v[106:109], v204 offset:96
	v_cvt_pk_bf16_f32 v219, v224, v225
	v_cvt_pk_bf16_f32 v220, v226, v227
	v_cvt_pk_bf16_f32 v221, v228, v229
	s_waitcnt lgkmcnt(2)
	v_mfma_f32_32x32x16_bf16 v[50:65], v[110:113], v[86:89], v[50:65]
	ds_read_b128 v[110:113], v202 offset:96
	v_exp_f32_e32 v230, v230
	v_exp_f32_e32 v231, v231
	v_exp_f32_e32 v232, v232
	s_waitcnt lgkmcnt(2)
	v_mfma_f32_32x32x16_bf16 v[66:81], v[158:161], v[86:89], v[66:81]
	v_exp_f32_e32 v233, v233
	v_exp_f32_e32 v234, v234
	v_exp_f32_e32 v235, v235
	s_waitcnt lgkmcnt(1)
	v_mfma_f32_32x32x16_bf16 v[50:65], v[106:109], v[82:85], v[50:65]
	v_exp_f32_e32 v236, v236
	v_exp_f32_e32 v237, v237
	v_cvt_pk_bf16_f32 v230, v230, v231
	s_waitcnt lgkmcnt(0)
	v_mfma_f32_32x32x16_bf16 v[66:81], v[110:113], v[82:85], v[66:81]
	v_cvt_pk_bf16_f32 v231, v232, v233
	v_cvt_pk_bf16_f32 v232, v234, v235
	v_cvt_pk_bf16_f32 v233, v236, v237
	v_mfma_f32_32x32x16_bf16 v[2:17], v[206:209], v[214:217], v[2:17]
	ds_read2_b64 v[206:209], v123 offset0:132 offset1:134
	v_exp_f32_e32 v238, v238
	v_exp_f32_e32 v239, v239
	v_exp_f32_e32 v240, v240
	v_mfma_f32_32x32x16_bf16 v[18:33], v[210:213], v[214:217], v[18:33]
	ds_read2_b64 v[210:213], v125 offset0:164 offset1:166
	v_exp_f32_e32 v241, v241
	v_exp_f32_e32 v242, v242
	v_exp_f32_e32 v243, v243
	v_mfma_f32_4x4x4_16b_bf16 v[34:37], v[118:119], v[214:215], v[34:37]
	v_mfma_f32_4x4x4_16b_bf16 v[38:41], v[118:119], v[216:217], v[38:41]
	v_exp_f32_e32 v244, v244
	v_exp_f32_e32 v245, v245
	s_waitcnt lgkmcnt(1)
	v_mfma_f32_32x32x16_bf16 v[2:17], v[206:209], v[218:221], v[2:17]
	ds_read2_b64 v[206:209], v123 offset0:136 offset1:138
	v_cvt_pk_bf16_f32 v234, v238, v239
	v_cvt_pk_bf16_f32 v235, v240, v241
	v_cvt_pk_bf16_f32 v236, v242, v243
	s_waitcnt lgkmcnt(1)
	v_mfma_f32_32x32x16_bf16 v[18:33], v[210:213], v[218:221], v[18:33]
	ds_read2_b64 v[210:213], v125 offset0:168 offset1:170
	v_cvt_pk_bf16_f32 v237, v244, v245
	v_mfma_f32_4x4x4_16b_bf16 v[34:37], v[118:119], v[218:219], v[34:37]
	v_mfma_f32_4x4x4_16b_bf16 v[38:41], v[118:119], v[220:221], v[38:41]
	s_waitcnt vmcnt(1)
	ds_write_b128 v201, v[98:101] offset:18432
	s_waitcnt vmcnt(0)
	ds_write2_b64 v129, v[102:103], v[104:105] offset1:1
	s_waitcnt lgkmcnt(3)
	v_mfma_f32_32x32x16_bf16 v[2:17], v[206:209], v[230:233], v[2:17]
	ds_read2_b64 v[206:209], v123 offset0:140 offset1:142
	v_exp_f32_e32 v50, v50
	v_exp_f32_e32 v51, v51
	v_exp_f32_e32 v52, v52
	s_waitcnt lgkmcnt(3)
	v_mfma_f32_32x32x16_bf16 v[18:33], v[210:213], v[230:233], v[18:33]
	ds_read2_b64 v[210:213], v125 offset0:172 offset1:174
	v_exp_f32_e32 v53, v53
	v_exp_f32_e32 v54, v54
	v_mfma_f32_4x4x4_16b_bf16 v[34:37], v[118:119], v[230:231], v[34:37]
	v_mfma_f32_4x4x4_16b_bf16 v[38:41], v[118:119], v[232:233], v[38:41]
	s_waitcnt lgkmcnt(1)
	v_mfma_f32_32x32x16_bf16 v[2:17], v[206:209], v[234:237], v[2:17]
	v_exp_f32_e32 v55, v55
	v_exp_f32_e32 v56, v56
	v_exp_f32_e32 v57, v57
	s_waitcnt lgkmcnt(0)
	v_mfma_f32_32x32x16_bf16 v[18:33], v[210:213], v[234:237], v[18:33]
	v_cvt_pk_bf16_f32 v50, v50, v51
	v_cvt_pk_bf16_f32 v51, v52, v53
	v_cvt_pk_bf16_f32 v52, v54, v55
	v_mfma_f32_4x4x4_16b_bf16 v[34:37], v[118:119], v[234:235], v[34:37]
	v_mfma_f32_4x4x4_16b_bf16 v[38:41], v[118:119], v[236:237], v[38:41]
	v_cvt_pk_bf16_f32 v53, v56, v57
	s_add_i32 s20, s20, 2
	s_cmp_lg_u32 s20, 36
	s_waitcnt lgkmcnt(0)
	s_barrier
	s_cbranch_scc1 .LBB0_167
	s_setprio 0
	s_nop 0
	s_nop 0
	s_nop 0
	s_nop 0
	s_nop 0
	s_nop 0
	s_nop 0
	s_nop 0
	s_nop 0
	s_nop 0
	s_nop 0
	s_nop 0
	s_nop 0
	s_nop 0
	s_nop 0
	s_nop 0
	s_nop 0
	s_nop 0
	s_nop 0
	s_nop 0
	s_nop 0
	s_nop 0
	s_nop 0
	s_nop 0
	s_nop 0
	s_nop 0
	s_nop 0
	global_load_dwordx4 v[214:217], v[154:155], off offset:1280
	global_load_dwordx4 v[218:221], v[150:151], off offset:1280
	global_load_dwordx4 v[222:225], v[142:143], off offset:1280
	global_load_dwordx4 v[226:229], v[138:139], off offset:1280
	s_mov_b64 s[4:5], 0x2000
	s_mov_b64 s[38:39], 0x80
	s_nop 15
	v_readlane_b32 s89, v248, 3
	v_add_f32_e32 v34, v34, v38
	s_nop 0
	ds_bpermute_b32 v35, v188, v34
	s_waitcnt lgkmcnt(0)
	v_add_f32_e32 v34, v34, v35
	s_nop 0
	v_div_scale_f32 v0, s[20:21], v34, v34, 1.0
	v_rcp_f32_e32 v35, v0
	s_waitcnt lgkmcnt(0)
	s_barrier
; #define LAS __attribute__((address_space(3)))
; __device__ __forceinline__ unsigned pk2(float lo, float hi) { f32x2_t v = {lo, hi}; bf16x2_t b = __builtin_convertvector(v, bf16x2_t); return __builtin_bit_cast(unsigned, b); }
; __device__ __forceinline__ float silu_f(float v) { return v * __builtin_amdgcn_rcpf(1.0f + __expf(-v)); }
; template <bool TRACK> ...
;     ...
;     const float ltot = TRACK ? lsum + __shfl_xor(lsum, 32) : lacc[0]; const float inv = 1.0f / ltot;
;     {
;         LAS unsigned char* scr = lds + 40960 + wave * 8704;
; #pragma unroll
;         for (int dh = 0; dh < 2; ++dh)
; #pragma unroll
;             for (int rg = 0; rg < 4; ++rg) { const int d = dh * 32 + 8 * rg + 4 * hi;
;                 f32x4 ov; ov.x = (dh == 0 ? o0[4 * rg] : o1[4 * rg]) * inv; ov.y = (dh == 0 ? o0[4 * rg + 1] : o1[4 * rg + 1]) * inv; ov.z = (dh == 0 ? o0[4 * rg + 2] : o1[4 * rg + 2]) * inv; ov.w = (dh == 0 ? o0[4 * rg + 3] : o1[4 * rg + 3]) * inv;
;                 *(LAS f32x4*)(scr + r32 * 272 + d * 4) = ov; }
;         const int pc = lane & 7;
; #pragma unroll
;         for (int i = 0; i < 4; ++i) { const int rw = i * 8 + (lane >> 3), row = wave * 32 + rw;
;             const f32x4 oa = *(const LAS f32x4*)(scr + rw * 272 + pc * 32), ob = *(const LAS f32x4*)(scr + rw * 272 + pc * 32 + 16);
;             float gv[8]; unpack8(*(const u32x4*)(gate + (size_t)row * INW + 8 * pc), gv);
;             u32x4 w; w.x = pk2(oa.x * silu_f(gv[0]), oa.y * silu_f(gv[1])); w.y = pk2(oa.z * silu_f(gv[2]), oa.w * silu_f(gv[3]));
;             w.z = pk2(ob.x * silu_f(gv[4]), ob.y * silu_f(gv[5])); w.w = pk2(ob.z * silu_f(gv[6]), ob.w * silu_f(gv[7]));
;             *(u32x4*)(outp + (size_t)row * DM + 8 * pc) = w; }
	v_fma_f32 v36, -v0, v35, 1.0
	v_fmac_f32_e32 v35, v36, v35
	v_div_scale_f32 v36, vcc, 1.0, v34, 1.0
	v_mul_f32_e32 v37, v36, v35
	v_fma_f32 v38, -v0, v37, v36
	v_fmac_f32_e32 v37, v38, v35
	v_fma_f32 v0, -v0, v37, v36
	v_div_fmas_f32 v0, v0, v35, v37
	v_div_fixup_f32 v0, v0, v34, 1.0
	s_nop 1
	v_mul_f32_e64 v2, v2, v0
	v_mul_f32_e64 v3, v3, v0
	v_pk_mul_f32 v[4:5], v[4:5], v[0:1] op_sel_hi:[1,0]
	v_add_u32_e32 v34, v198, v156
	ds_write_b128 v34, v[2:5] offset:40960
	v_pk_mul_f32 v[2:3], v[6:7], v[0:1] op_sel_hi:[1,0]
	v_pk_mul_f32 v[4:5], v[8:9], v[0:1] op_sel_hi:[1,0]
	ds_write_b128 v34, v[2:5] offset:40992
	v_pk_mul_f32 v[2:3], v[10:11], v[0:1] op_sel_hi:[1,0]
	v_pk_mul_f32 v[4:5], v[12:13], v[0:1] op_sel_hi:[1,0]
	ds_write_b128 v34, v[2:5] offset:41024
	v_pk_mul_f32 v[2:3], v[14:15], v[0:1] op_sel_hi:[1,0]
	v_pk_mul_f32 v[4:5], v[16:17], v[0:1] op_sel_hi:[1,0]
	ds_write_b128 v34, v[2:5] offset:41056
	v_pk_mul_f32 v[2:3], v[18:19], v[0:1] op_sel_hi:[1,0]
	v_pk_mul_f32 v[4:5], v[20:21], v[0:1] op_sel_hi:[1,0]
	ds_write_b128 v34, v[2:5] offset:41088
	v_pk_mul_f32 v[2:3], v[22:23], v[0:1] op_sel_hi:[1,0]
	v_pk_mul_f32 v[4:5], v[24:25], v[0:1] op_sel_hi:[1,0]
	ds_write_b128 v34, v[2:5] offset:41120
	v_pk_mul_f32 v[2:3], v[26:27], v[0:1] op_sel_hi:[1,0]
	v_pk_mul_f32 v[4:5], v[28:29], v[0:1] op_sel_hi:[1,0]
	ds_write_b128 v34, v[2:5] offset:41152
	v_pk_mul_f32 v[2:3], v[30:31], v[0:1] op_sel_hi:[1,0]
	v_pk_mul_f32 v[4:5], v[32:33], v[0:1] op_sel_hi:[1,0]
	ds_write_b128 v34, v[2:5] offset:41184
	v_add_u32_e32 v0, v192, v193
	ds_read_b128 v[6:9], v0 offset:40960
	ds_read_b128 v[2:5], v0 offset:40976
	s_waitcnt vmcnt(3)
	v_lshlrev_b32_e32 v14, 16, v214
	v_and_b32_e32 v15, 0xffff0000, v214
	v_mul_f32_e32 v214, 0xbfb8aa3b, v14
	v_exp_f32_e32 v214, v214
	s_nop 0
	v_add_f32_e32 v214, 1.0, v214
	v_rcp_f32_e32 v16, v214
	v_mul_f32_e32 v214, 0xbfb8aa3b, v15
	v_exp_f32_e32 v214, v214
	s_nop 0
	v_add_f32_e32 v214, 1.0, v214
	v_rcp_f32_e32 v17, v214
	v_lshlrev_b32_e32 v214, 16, v215
	v_and_b32_e32 v215, 0xffff0000, v215
	v_pk_mul_f32 v[14:15], v[16:17], v[14:15]
	s_waitcnt lgkmcnt(1)
	v_pk_mul_f32 v[6:7], v[6:7], v[14:15]
	s_nop 0
	v_cvt_pk_bf16_f32 v6, v6, v7
	v_mul_f32_e32 v7, 0xbfb8aa3b, v214
	v_exp_f32_e32 v7, v7
	s_nop 0
	v_add_f32_e32 v7, 1.0, v7
	v_rcp_f32_e32 v14, v7
	v_mul_f32_e32 v7, 0xbfb8aa3b, v215
	v_exp_f32_e32 v7, v7
	s_nop 0
	v_add_f32_e32 v7, 1.0, v7
	v_rcp_f32_e32 v15, v7
	s_nop 0
	v_pk_mul_f32 v[214:215], v[14:15], v[214:215]
	s_nop 0
	v_pk_mul_f32 v[8:9], v[8:9], v[214:215]
	s_nop 0
	v_cvt_pk_bf16_f32 v7, v8, v9
	v_lshlrev_b32_e32 v8, 16, v216
	v_and_b32_e32 v9, 0xffff0000, v216
	v_mul_f32_e32 v214, 0xbfb8aa3b, v8
	v_mul_f32_e32 v215, 0xbfb8aa3b, v9
	v_exp_f32_e32 v214, v214
	v_exp_f32_e32 v215, v215
	v_add_f32_e32 v214, 1.0, v214
	v_add_f32_e32 v215, 1.0, v215
	v_rcp_f32_e32 v214, v214
	v_rcp_f32_e32 v215, v215
	s_nop 0
	v_pk_mul_f32 v[8:9], v[214:215], v[8:9]
	s_waitcnt lgkmcnt(0)
	v_pk_mul_f32 v[2:3], v[2:3], v[8:9]
	s_nop 0
	v_cvt_pk_bf16_f32 v8, v2, v3
	v_lshlrev_b32_e32 v2, 16, v217
	v_mul_f32_e32 v9, 0xbfb8aa3b, v2
	v_exp_f32_e32 v9, v9
	v_and_b32_e32 v3, 0xffff0000, v217
	v_add_f32_e32 v9, 1.0, v9
	v_rcp_f32_e32 v214, v9
	v_mul_f32_e32 v9, 0xbfb8aa3b, v3
	v_exp_f32_e32 v9, v9
	s_nop 0
	v_add_f32_e32 v9, 1.0, v9
	v_rcp_f32_e32 v215, v9
	s_nop 0
	v_pk_mul_f32 v[2:3], v[214:215], v[2:3]
	s_nop 0
	v_pk_mul_f32 v[2:3], v[4:5], v[2:3]
	s_nop 0
	v_cvt_pk_bf16_f32 v9, v2, v3
	global_store_dwordx4 v[152:153], v[6:9], off
	ds_read_b128 v[6:9], v0 offset:43136
	ds_read_b128 v[2:5], v0 offset:43152
	s_waitcnt vmcnt(3)
	v_lshlrev_b32_e32 v14, 16, v218
	v_and_b32_e32 v15, 0xffff0000, v218
	v_mul_f32_e32 v218, 0xbfb8aa3b, v14
	v_exp_f32_e32 v218, v218
	s_nop 0
	v_add_f32_e32 v218, 1.0, v218
	v_rcp_f32_e32 v16, v218
	v_mul_f32_e32 v218, 0xbfb8aa3b, v15
	v_exp_f32_e32 v218, v218
	s_nop 0
	v_add_f32_e32 v218, 1.0, v218
	v_rcp_f32_e32 v17, v218
	v_lshlrev_b32_e32 v218, 16, v219
	v_and_b32_e32 v219, 0xffff0000, v219
	v_pk_mul_f32 v[14:15], v[16:17], v[14:15]
	s_waitcnt lgkmcnt(1)
	v_pk_mul_f32 v[6:7], v[6:7], v[14:15]
	s_nop 0
	v_cvt_pk_bf16_f32 v6, v6, v7
	v_mul_f32_e32 v7, 0xbfb8aa3b, v218
	v_exp_f32_e32 v7, v7
	s_nop 0
	v_add_f32_e32 v7, 1.0, v7
	v_rcp_f32_e32 v14, v7
	v_mul_f32_e32 v7, 0xbfb8aa3b, v219
	v_exp_f32_e32 v7, v7
	s_nop 0
	v_add_f32_e32 v7, 1.0, v7
	v_rcp_f32_e32 v15, v7
	s_nop 0
	v_pk_mul_f32 v[218:219], v[14:15], v[218:219]
	s_nop 0
	v_pk_mul_f32 v[8:9], v[8:9], v[218:219]
	s_nop 0
	v_cvt_pk_bf16_f32 v7, v8, v9
	v_lshlrev_b32_e32 v8, 16, v220
	v_and_b32_e32 v9, 0xffff0000, v220
	v_mul_f32_e32 v218, 0xbfb8aa3b, v8
	v_mul_f32_e32 v219, 0xbfb8aa3b, v9
	v_exp_f32_e32 v218, v218
	v_exp_f32_e32 v219, v219
	v_add_f32_e32 v218, 1.0, v218
	v_add_f32_e32 v219, 1.0, v219
	v_rcp_f32_e32 v218, v218
	v_rcp_f32_e32 v219, v219
	s_nop 0
	v_pk_mul_f32 v[8:9], v[218:219], v[8:9]
	s_waitcnt lgkmcnt(0)
; #define LAS __attribute__((address_space(3)))
; __device__ __forceinline__ unsigned pk2(float lo, float hi) { f32x2_t v = {lo, hi}; bf16x2_t b = __builtin_convertvector(v, bf16x2_t); return __builtin_bit_cast(unsigned, b); }
; __device__ __forceinline__ float silu_f(float v) { return v * __builtin_amdgcn_rcpf(1.0f + __expf(-v)); }
; template <bool TRACK> ...
;     ...
;         const int pc = lane & 7;
; #pragma unroll
;         for (int i = 0; i < 4; ++i) { const int rw = i * 8 + (lane >> 3), row = wave * 32 + rw;
;             const f32x4 oa = *(const LAS f32x4*)(scr + rw * 272 + pc * 32), ob = *(const LAS f32x4*)(scr + rw * 272 + pc * 32 + 16);
;             float gv[8]; unpack8(*(const u32x4*)(gate + (size_t)row * INW + 8 * pc), gv);
;             u32x4 w; w.x = pk2(oa.x * silu_f(gv[0]), oa.y * silu_f(gv[1])); w.y = pk2(oa.z * silu_f(gv[2]), oa.w * silu_f(gv[3]));
;             w.z = pk2(ob.x * silu_f(gv[4]), ob.y * silu_f(gv[5])); w.w = pk2(ob.z * silu_f(gv[6]), ob.w * silu_f(gv[7]));
;             *(u32x4*)(outp + (size_t)row * DM + 8 * pc) = w; }
	v_pk_mul_f32 v[2:3], v[2:3], v[8:9]
	s_nop 0
	v_cvt_pk_bf16_f32 v8, v2, v3
	v_lshlrev_b32_e32 v2, 16, v221
	v_mul_f32_e32 v9, 0xbfb8aa3b, v2
	v_exp_f32_e32 v9, v9
	v_and_b32_e32 v3, 0xffff0000, v221
	v_add_f32_e32 v9, 1.0, v9
	v_rcp_f32_e32 v218, v9
	v_mul_f32_e32 v9, 0xbfb8aa3b, v3
	v_exp_f32_e32 v9, v9
	s_nop 0
	v_add_f32_e32 v9, 1.0, v9
	v_rcp_f32_e32 v219, v9
	s_nop 0
	v_pk_mul_f32 v[2:3], v[218:219], v[2:3]
	s_nop 0
	v_pk_mul_f32 v[2:3], v[4:5], v[2:3]
	s_nop 0
	v_cvt_pk_bf16_f32 v9, v2, v3
	global_store_dwordx4 v[144:145], v[6:9], off
	ds_read_b128 v[6:9], v0 offset:45312
	ds_read_b128 v[2:5], v0 offset:45328
	s_waitcnt vmcnt(3)
	v_lshlrev_b32_e32 v14, 16, v222
	v_and_b32_e32 v15, 0xffff0000, v222
	v_mul_f32_e32 v222, 0xbfb8aa3b, v14
	v_exp_f32_e32 v222, v222
	s_nop 0
	v_add_f32_e32 v222, 1.0, v222
	v_rcp_f32_e32 v16, v222
	v_mul_f32_e32 v222, 0xbfb8aa3b, v15
	v_exp_f32_e32 v222, v222
	s_nop 0
	v_add_f32_e32 v222, 1.0, v222
	v_rcp_f32_e32 v17, v222
	v_lshlrev_b32_e32 v222, 16, v223
	v_and_b32_e32 v223, 0xffff0000, v223
	v_pk_mul_f32 v[14:15], v[16:17], v[14:15]
	s_waitcnt lgkmcnt(1)
	v_pk_mul_f32 v[6:7], v[6:7], v[14:15]
	s_nop 0
	v_cvt_pk_bf16_f32 v6, v6, v7
	v_mul_f32_e32 v7, 0xbfb8aa3b, v222
	v_exp_f32_e32 v7, v7
	s_nop 0
	v_add_f32_e32 v7, 1.0, v7
	v_rcp_f32_e32 v14, v7
	v_mul_f32_e32 v7, 0xbfb8aa3b, v223
	v_exp_f32_e32 v7, v7
	s_nop 0
	v_add_f32_e32 v7, 1.0, v7
	v_rcp_f32_e32 v15, v7
	s_nop 0
	v_pk_mul_f32 v[222:223], v[14:15], v[222:223]
	s_nop 0
	v_pk_mul_f32 v[8:9], v[8:9], v[222:223]
	s_nop 0
	v_cvt_pk_bf16_f32 v7, v8, v9
	v_lshlrev_b32_e32 v8, 16, v224
	v_and_b32_e32 v9, 0xffff0000, v224
	v_mul_f32_e32 v222, 0xbfb8aa3b, v8
	v_mul_f32_e32 v223, 0xbfb8aa3b, v9
	v_exp_f32_e32 v222, v222
	v_exp_f32_e32 v223, v223
	v_add_f32_e32 v222, 1.0, v222
	v_add_f32_e32 v223, 1.0, v223
	v_rcp_f32_e32 v222, v222
	v_rcp_f32_e32 v223, v223
	s_nop 0
	v_pk_mul_f32 v[8:9], v[222:223], v[8:9]
	s_waitcnt lgkmcnt(0)
	v_pk_mul_f32 v[2:3], v[2:3], v[8:9]
	s_nop 0
	v_cvt_pk_bf16_f32 v8, v2, v3
	v_lshlrev_b32_e32 v2, 16, v225
	v_mul_f32_e32 v9, 0xbfb8aa3b, v2
	v_exp_f32_e32 v9, v9
	v_and_b32_e32 v3, 0xffff0000, v225
	v_add_f32_e32 v9, 1.0, v9
	v_rcp_f32_e32 v222, v9
	v_mul_f32_e32 v9, 0xbfb8aa3b, v3
	v_exp_f32_e32 v9, v9
	s_nop 0
	v_add_f32_e32 v9, 1.0, v9
	v_rcp_f32_e32 v223, v9
	s_nop 0
	v_pk_mul_f32 v[2:3], v[222:223], v[2:3]
	s_nop 0
	v_pk_mul_f32 v[2:3], v[4:5], v[2:3]
	s_nop 0
	v_cvt_pk_bf16_f32 v9, v2, v3
	global_store_dwordx4 v[140:141], v[6:9], off
	ds_read_b128 v[6:9], v0 offset:47488
	ds_read_b128 v[2:5], v0 offset:47504
	s_waitcnt vmcnt(3)
	v_lshlrev_b32_e32 v14, 16, v226
	v_mul_f32_e32 v0, 0xbfb8aa3b, v14
	v_exp_f32_e32 v0, v0
	v_and_b32_e32 v15, 0xffff0000, v226
	v_lshlrev_b32_e32 v226, 16, v227
	v_and_b32_e32 v227, 0xffff0000, v227
	v_add_f32_e32 v0, 1.0, v0
	v_rcp_f32_e32 v16, v0
	v_mul_f32_e32 v0, 0xbfb8aa3b, v15
	v_exp_f32_e32 v0, v0
	s_nop 0
	v_add_f32_e32 v0, 1.0, v0
	v_rcp_f32_e32 v17, v0
	v_mul_f32_e32 v0, 0xbfb8aa3b, v226
	v_exp_f32_e32 v0, v0
	v_pk_mul_f32 v[14:15], v[16:17], v[14:15]
	s_waitcnt lgkmcnt(1)
	v_pk_mul_f32 v[6:7], v[6:7], v[14:15]
	v_add_f32_e32 v0, 1.0, v0
	v_rcp_f32_e32 v14, v0
	v_mul_f32_e32 v0, 0xbfb8aa3b, v227
	v_exp_f32_e32 v0, v0
	v_cvt_pk_bf16_f32 v6, v6, v7
	v_add_f32_e32 v0, 1.0, v0
	v_rcp_f32_e32 v15, v0
	s_nop 0
	v_pk_mul_f32 v[226:227], v[14:15], v[226:227]
	s_nop 0
	v_pk_mul_f32 v[8:9], v[8:9], v[226:227]
	s_nop 0
	v_cvt_pk_bf16_f32 v7, v8, v9
	v_lshlrev_b32_e32 v8, 16, v228
	v_mul_f32_e32 v0, 0xbfb8aa3b, v8
	v_exp_f32_e32 v0, v0
	v_and_b32_e32 v9, 0xffff0000, v228
	v_add_f32_e32 v0, 1.0, v0
	v_rcp_f32_e32 v226, v0
	v_mul_f32_e32 v0, 0xbfb8aa3b, v9
	v_exp_f32_e32 v0, v0
	s_nop 0
	v_add_f32_e32 v0, 1.0, v0
	v_rcp_f32_e32 v227, v0
	s_nop 0
	v_pk_mul_f32 v[8:9], v[226:227], v[8:9]
	s_waitcnt lgkmcnt(0)
	v_pk_mul_f32 v[2:3], v[2:3], v[8:9]
	s_nop 0
	v_cvt_pk_bf16_f32 v8, v2, v3
	v_lshlrev_b32_e32 v2, 16, v229
	v_mul_f32_e32 v0, 0xbfb8aa3b, v2
	v_exp_f32_e32 v0, v0
	v_and_b32_e32 v3, 0xffff0000, v229
	v_add_f32_e32 v0, 1.0, v0
	v_rcp_f32_e32 v226, v0
	v_mul_f32_e32 v0, 0xbfb8aa3b, v3
	v_exp_f32_e32 v0, v0
	s_nop 0
	v_add_f32_e32 v0, 1.0, v0
	v_rcp_f32_e32 v227, v0
	s_nop 0
	v_pk_mul_f32 v[2:3], v[226:227], v[2:3]
	s_nop 0
	v_pk_mul_f32 v[2:3], v[4:5], v[2:3]
	s_nop 0
	v_cvt_pk_bf16_f32 v9, v2, v3
	global_store_dwordx4 v[136:137], v[6:9], off
